# Mamba item: dt prefetch no longer waited on right after issue (raw bf16 kept in a register, converted at first use next round), on top of the batched SB epilogue, queue-resident K/V projection tiles a
# speedup vs baseline: 1.0145x; 1.0037x over previous
; DI float bf2f(u16 v) { return __uint_as_float(((unsigned)v) << 16); }
; DI unsigned uidx(long row, int col) { return ((unsigned)(col >> 6) * (unsigned)MT + (unsigned)row) * 64u + (unsigned)(col & 63); }
; DI void mamba_item(int wv, const Params& p, int layer, int b, int h, bool samp, char* smc, bool dry) {
;     ...
;   const u16* xsp = U + uidx(row0, cXBC + h * 64 + zc);
;   const u16* zp = U + uidx(row0, cZB + h * 64 + zc);
;   const u16* bp0 = U + uidx(row0, cXBC + 768 + g * 128 + bc);
;   const u16* cp0 = U + uidx(row0, cXBC + 1024 + g * 128 + bc);
;   const u16* dtp = U + uidx(row0, cDT + h);
;     ...
;     if (tid < 32) dtr = (t0 + tid < T) ? bf2f(dtp[(long)(t0 + tid) * 64]) : 0.f;
.LBB0_571:
	s_or_b64 exec, exec, s[0:1]
	s_add_i32 s0, s88, 0x1880
	s_lshr_b32 s0, s0, 6
	s_mul_i32 s0, s0, 0x10200
	s_add_i32 s0, s0, s30
	s_lshl_b32 s0, s0, 6
	s_and_b32 s1, s88, 63
	s_or_b32 s54, s0, s1
	s_lshl_b64 s[0:1], s[54:55], 1
	s_add_u32 s84, s76, s0
	v_cmp_gt_i32_e64 s[6:7], 32, v68
	v_cmp_gt_i32_e32 vcc, s2, v68
	s_addc_u32 s85, s77, s1
	s_and_b64 s[12:13], s[6:7], vcc
	v_mov_b32_e32 v69, 0
	s_and_saveexec_b64 s[0:1], s[12:13]
	s_cbranch_execz .LBB0_573
	v_ashrrev_i32_e32 v69, 31, v68
	v_lshlrev_b64 v[2:3], 7, v[68:69]
	v_lshl_add_u64 v[2:3], s[84:85], 0, v[2:3]
	global_load_ushort v1, v[2:3], off
	s_waitcnt vmcnt(0)
	v_mov_b32_e32 v69, v1

; DI float softplusf(float x) { return fmaxf(x, 0.f) + __logf(1.f + __expf(-fabsf(x))); }
; DI void mamba_item(int wv, const Params& p, int layer, int b, int h, bool samp, char* smc, bool dry) {
;     ...
;     if (tid < 32) {
;       const int t = tid;
;       float dt = (t < nv) ? softplusf(dtr + dtb) : 0.f;
.LBB0_575:
	s_and_saveexec_b64 s[30:31], s[6:7]
	s_cbranch_execz .LBB0_579
	v_cmp_gt_i32_e32 vcc, s3, v68
	v_mov_b32_e32 v1, 0
	s_and_saveexec_b64 s[34:35], vcc
	s_cbranch_execz .LBB0_578
	s_waitcnt vmcnt(0)
	v_lshlrev_b32_e32 v69, 16, v69
	v_add_f32_e32 v1, v100, v69
	v_mul_f32_e64 v2, |v1|, s52
	v_exp_f32_e32 v2, v2
	v_max_f32_e32 v1, 0, v1
	v_add_f32_e32 v2, 1.0, v2
	v_cmp_gt_f32_e32 vcc, s72, v2
	s_nop 1
	v_cndmask_b32_e64 v3, 0, 32, vcc
	v_ldexp_f32 v2, v2, v3
	v_log_f32_e32 v2, v2
	s_nop 0
	v_mul_f32_e32 v3, 0x3f317217, v2
	v_fma_f32 v3, v2, s53, -v3
	v_fmac_f32_e32 v3, 0x3377d1cf, v2
	v_fmac_f32_e32 v3, 0x3f317217, v2
	v_cmp_lt_f32_e64 s[0:1], |v2|, s95
	s_nop 1
	v_cndmask_b32_e64 v2, v2, v3, s[0:1]
	v_cndmask_b32_e32 v3, 0, v210, vcc
	v_sub_f32_e32 v2, v2, v3
	v_add_f32_e32 v1, v1, v2

; DI float bf2f(u16 v) { return __uint_as_float(((unsigned)v) << 16); }
; DI void mamba_item(int wv, const Params& p, int layer, int b, int h, bool samp, char* smc, bool dry) {
;     ...
;     if (tid < 32) dtr = (t0 + tid < T) ? bf2f(dtp[(long)(t0 + tid) * 64]) : 0.f;
;     ...
;     if (t0 + 32 < T) issue(t0 + 32);
.LBB0_594:
	s_or_b64 exec, exec, s[0:1]
	s_and_saveexec_b64 s[0:1], s[6:7]
	s_cbranch_execz .LBB0_598
	v_add_u32_e32 v2, s4, v81
	v_cmp_gt_i32_e32 vcc, s2, v2
	v_mov_b32_e32 v69, 0
	s_and_saveexec_b64 s[30:31], vcc
	s_cbranch_execz .LBB0_597
	v_ashrrev_i32_e32 v3, 31, v2
	v_lshlrev_b64 v[2:3], 7, v[2:3]
	v_lshl_add_u64 v[2:3], s[84:85], 0, v[2:3]
	global_load_ushort v69, v[2:3], off
